# norm phases after a residual GEMM visit the most recently written rows first (row permutation of the sweep)
# baseline (speedup 1.0000x reference)
.LBB0_420:
	v_add_u32_e32 v75, s94, v54
	v_mov_b32_e32 v100, v54
	v_xor_b32_e32 v102, 0xc000, v100
	v_and_b32_e32 v103, 0x7ff, v100
	v_lshrrev_b32_e32 v102, 3, v102
	v_lshlrev_b32_e32 v54, 2, v100
	v_and_b32_e32 v102, 0x1800, v102
	v_and_b32_e32 v54, 0xe000, v54
	v_or3_b32 v54, v54, v102, v103
	v_ashrrev_i32_e32 v55, 31, v54
	v_lshlrev_b64 v[0:1], 12, v[54:55]
	v_cmp_gt_i32_e32 vcc, s2, v75
	v_lshl_add_u64 v[0:1], v[38:39], 0, v[0:1]
	global_load_dwordx4 v[28:31], v[0:1], off nt
	global_load_dwordx4 v[20:23], v[0:1], off offset:1024 nt
	global_load_dwordx4 v[4:7], v[0:1], off offset:3072 nt
	global_load_dwordx4 v[12:15], v[0:1], off offset:2048 nt
	v_xor_b32_e32 v102, 0xc000, v75
	v_and_b32_e32 v103, 0x7ff, v75
	v_lshrrev_b32_e32 v102, 3, v102
	v_lshlrev_b32_e32 v101, 2, v75
	v_and_b32_e32 v102, 0x1800, v102
	v_and_b32_e32 v101, 0xe000, v101
	v_or3_b32 v101, v101, v102, v103
	v_cndmask_b32_e32 v56, v54, v101, vcc
	v_ashrrev_i32_e32 v57, 31, v56
	v_lshlrev_b64 v[0:1], 12, v[56:57]
	v_lshl_add_u64 v[32:33], v[38:39], 0, v[0:1]
	global_load_dwordx4 v[24:27], v[32:33], off nt
	global_load_dwordx4 v[16:19], v[32:33], off offset:1024 nt
	global_load_dwordx4 v[0:3], v[32:33], off offset:3072 nt
	global_load_dwordx4 v[8:11], v[32:33], off offset:2048 nt
	s_waitcnt vmcnt(7)
	v_pk_mul_f32 v[32:33], v[30:31], v[30:31]
	v_pk_mul_f32 v[34:35], v[28:29], v[28:29]
	s_waitcnt vmcnt(6)
	v_pk_mul_f32 v[58:59], v[22:23], v[22:23]
	v_pk_mul_f32 v[60:61], v[20:21], v[20:21]
	s_waitcnt vmcnt(4)
	v_mul_f32_e32 v62, v15, v15
	v_pk_mov_b32 v[64:65], v[34:35], v[32:33] op_sel:[1,0]
	v_mov_b32_e32 v35, v33
	v_pk_mov_b32 v[32:33], v[60:61], v[58:59] op_sel:[1,0]
	v_mov_b32_e32 v61, v59
	v_mul_f32_e32 v78, v7, v7
	v_mul_f32_e32 v36, v13, v13
	v_pk_fma_f32 v[62:63], v[14:15], v[14:15], v[62:63] op_sel_hi:[1,1,0]
	v_pk_add_f32 v[34:35], v[64:65], v[34:35]
	s_waitcnt vmcnt(3)
	v_pk_mul_f32 v[64:65], v[26:27], v[26:27]
	v_pk_mul_f32 v[66:67], v[24:25], v[24:25]
	v_pk_add_f32 v[32:33], v[32:33], v[60:61]
	s_waitcnt vmcnt(2)
	v_pk_mul_f32 v[60:61], v[18:19], v[18:19]
	v_pk_mul_f32 v[68:69], v[16:17], v[16:17]
	v_mul_f32_e32 v51, v4, v4
	v_mul_f32_e32 v77, v5, v5
	v_mul_f32_e32 v76, v6, v6
	v_pk_fma_f32 v[58:59], v[12:13], v[12:13], v[36:37] op_sel_hi:[1,1,0]
	v_mov_b32_e32 v63, v78
	v_pk_mov_b32 v[78:79], v[66:67], v[64:65] op_sel:[1,0]
	v_mov_b32_e32 v67, v65
	v_pk_mov_b32 v[64:65], v[68:69], v[60:61] op_sel:[1,0]
	v_mov_b32_e32 v69, v61
	v_pk_add_f32 v[34:35], v[34:35], v[34:35] op_sel:[0,1] op_sel_hi:[1,0]
	v_pk_add_f32 v[32:33], v[32:33], v[32:33] op_sel:[0,1] op_sel_hi:[1,0]
	v_mov_b32_e32 v59, v76
	s_waitcnt vmcnt(0)
	v_mul_f32_e32 v36, v9, v9
	v_mul_f32_e32 v76, v11, v11
	v_pk_add_f32 v[66:67], v[78:79], v[66:67]
	v_pk_add_f32 v[64:65], v[64:65], v[68:69]
	v_mov_b32_e32 v35, v51
	v_mov_b32_e32 v33, v77
	v_mul_f32_e32 v80, v0, v0
	v_mul_f32_e32 v81, v1, v1
	v_mul_f32_e32 v82, v2, v2
	v_mul_f32_e32 v83, v3, v3
	v_pk_add_f32 v[58:59], v[58:59], v[62:63]
	v_pk_fma_f32 v[60:61], v[8:9], v[8:9], v[36:37] op_sel_hi:[1,1,0]
	v_pk_fma_f32 v[62:63], v[10:11], v[10:11], v[76:77] op_sel_hi:[1,1,0]
	v_pk_add_f32 v[32:33], v[34:35], v[32:33]
	v_pk_add_f32 v[34:35], v[66:67], v[66:67] op_sel:[0,1] op_sel_hi:[1,0]
	v_pk_add_f32 v[64:65], v[64:65], v[64:65] op_sel:[0,1] op_sel_hi:[1,0]
	v_mov_b32_e32 v61, v82
	v_mov_b32_e32 v63, v83
	v_pk_add_f32 v[32:33], v[32:33], v[58:59]
	v_mov_b32_e32 v35, v80
	v_mov_b32_e32 v65, v81
	v_pk_add_f32 v[60:61], v[60:61], v[62:63]
	v_add_f32_e32 v36, v32, v33
	v_pk_add_f32 v[32:33], v[34:35], v[64:65]
	ds_bpermute_b32 v34, v45, v36
	v_pk_add_f32 v[32:33], v[32:33], v[60:61]
	v_ashrrev_i32_e32 v51, 12, v54
	v_add_f32_e32 v32, v32, v33
	ds_bpermute_b32 v33, v45, v32
	s_waitcnt lgkmcnt(1)
	v_add_f32_e32 v36, v36, v34
	ds_bpermute_b32 v58, v47, v36
	v_mul_hi_i32_i24_e32 v59, 0x9000, v51
	s_waitcnt lgkmcnt(1)
	v_add_f32_e32 v60, v32, v33
	ds_bpermute_b32 v61, v47, v60
	s_waitcnt lgkmcnt(1)
	v_add_f32_e32 v36, v36, v58
	ds_bpermute_b32 v62, v49, v36
	v_mul_i32_i24_e32 v58, 0x9000, v51
	v_lshl_add_u64 v[58:59], s[8:9], 0, v[58:59]
	s_waitcnt lgkmcnt(1)
	v_add_f32_e32 v60, v60, v61
	ds_bpermute_b32 v61, v49, v60
	s_waitcnt lgkmcnt(1)
	v_add_f32_e32 v36, v36, v62
	global_load_dwordx4 v[32:35], v[42:43], off
	ds_bpermute_b32 v51, v70, v36
	s_waitcnt lgkmcnt(1)
	v_add_f32_e32 v62, v60, v61
	ds_bpermute_b32 v63, v70, v62
	v_lshl_add_u64 v[60:61], v[58:59], 0, s[12:13]
	v_lshl_add_u64 v[58:59], v[58:59], 0, s[14:15]
	v_lshl_add_u64 v[64:65], v[58:59], 0, v[52:53]
	s_waitcnt lgkmcnt(1)
	v_add_f32_e32 v36, v36, v51
	s_waitcnt lgkmcnt(0)
	v_add_f32_e32 v66, v62, v63
	v_lshl_add_u64 v[62:63], v[60:61], 0, v[52:53]
	global_load_dwordx4 v[76:79], v[62:63], off
	global_load_dwordx4 v[80:83], v[64:65], off
	ds_bpermute_b32 v51, v71, v36
	ds_bpermute_b32 v67, v71, v66
	s_waitcnt lgkmcnt(1)
	v_add_f32_e32 v36, v36, v51
	ds_bpermute_b32 v51, v72, v36
	s_waitcnt lgkmcnt(1)
	v_add_f32_e32 v66, v66, v67
	ds_bpermute_b32 v67, v72, v66
	s_waitcnt lgkmcnt(1)
	v_add_f32_e32 v36, v36, v51
	v_fmamk_f32 v36, v36, 0x3a800000, v73
	v_mul_f32_e32 v51, 0x4f800000, v36
	v_cmp_gt_f32_e32 vcc, s3, v36
	s_waitcnt lgkmcnt(0)
	v_add_f32_e32 v62, v66, v67
	s_waitcnt vmcnt(1)
	v_pk_add_f32 v[78:79], v[78:79], 1.0 op_sel_hi:[1,0]
	v_cndmask_b32_e32 v36, v36, v51, vcc
	v_fmamk_f32 v51, v62, 0x3a800000, v73
	v_sqrt_f32_e32 v62, v36
	v_mul_f32_e32 v63, 0x4f800000, v51
	v_cmp_gt_f32_e64 s[4:5], s3, v51
	v_pk_add_f32 v[76:77], v[76:77], 1.0 op_sel_hi:[1,0]
	v_add_u32_e32 v64, -1, v62
	v_cndmask_b32_e64 v51, v51, v63, s[4:5]
	v_sqrt_f32_e32 v63, v51
	v_add_u32_e32 v65, 1, v62
	v_fma_f32 v66, -v64, v62, v36
	v_fma_f32 v67, -v65, v62, v36
	v_cmp_ge_f32_e64 s[6:7], 0, v66
	v_add_u32_e32 v66, 1, v63
	s_nop 0
	v_cndmask_b32_e64 v62, v62, v64, s[6:7]
	v_add_u32_e32 v64, -1, v63
	v_cmp_lt_f32_e64 s[6:7], 0, v67
	v_fma_f32 v67, -v66, v63, v51
	s_nop 0
	v_cndmask_b32_e64 v62, v62, v65, s[6:7]
	v_fma_f32 v65, -v64, v63, v51
	v_mul_f32_e32 v68, 0x37800000, v62
	v_cmp_ge_f32_e64 s[6:7], 0, v65
	v_cndmask_b32_e32 v62, v62, v68, vcc
	v_cmp_lt_f32_e32 vcc, 0, v67
	v_cndmask_b32_e64 v63, v63, v64, s[6:7]
	s_nop 0
	v_cndmask_b32_e32 v63, v63, v66, vcc
	v_cmp_class_f32_e32 vcc, v36, v74
	s_nop 1
	v_cndmask_b32_e32 v36, v62, v36, vcc
	v_div_scale_f32 v64, s[6:7], v36, v36, 1.0
	v_rcp_f32_e32 v65, v64
	v_mul_f32_e32 v62, 0x37800000, v63
	v_cndmask_b32_e64 v62, v63, v62, s[4:5]
	v_div_scale_f32 v66, vcc, 1.0, v36, 1.0
	v_fma_f32 v63, -v64, v65, 1.0
	v_fmac_f32_e32 v65, v63, v65
	v_mul_f32_e32 v63, v66, v65
	v_cmp_class_f32_e64 s[4:5], v51, v74
	v_fma_f32 v67, -v64, v63, v66
	v_fmac_f32_e32 v63, v67, v65
	v_cndmask_b32_e64 v51, v62, v51, s[4:5]
	v_div_scale_f32 v62, s[4:5], v51, v51, 1.0
	v_fma_f32 v64, -v64, v63, v66
	v_rcp_f32_e32 v66, v62
	v_div_fmas_f32 v63, v64, v65, v63
	v_div_fixup_f32 v68, v63, v36, 1.0
	v_pk_mul_f32 v[30:31], v[30:31], v[68:69] op_sel_hi:[1,0]
	v_fma_f32 v36, -v62, v66, 1.0
	v_fmac_f32_e32 v66, v36, v66
	v_div_scale_f32 v36, vcc, 1.0, v51, 1.0
	v_mul_f32_e32 v63, v36, v66
	v_fma_f32 v64, -v62, v63, v36
	v_fmac_f32_e32 v63, v64, v66
	v_fma_f32 v36, -v62, v63, v36
	v_div_fmas_f32 v36, v36, v66, v63
	v_div_fixup_f32 v64, v36, v51, 1.0
	v_ashrrev_i32_e32 v36, 12, v56
	v_pk_mul_f32 v[28:29], v[28:29], v[68:69] op_sel_hi:[1,0]
	v_lshlrev_b64 v[62:63], 11, v[54:55]
	v_cmp_ne_u32_e32 vcc, v54, v56
	v_mul_hi_i32_i24_e32 v55, 0x9000, v36
	v_mul_i32_i24_e32 v54, 0x9000, v36
	v_pk_mul_f32 v[28:29], v[32:33], v[28:29]
	v_pk_mul_f32 v[30:31], v[34:35], v[30:31]
	v_lshl_add_u64 v[66:67], v[40:41], 0, v[62:63]
	v_lshlrev_b64 v[62:63], 11, v[56:57]
	v_lshl_add_u64 v[54:55], s[8:9], 0, v[54:55]
	s_waitcnt vmcnt(0)
	v_pk_fma_f32 v[30:31], v[78:79], v[30:31], v[82:83]
	v_pk_fma_f32 v[28:29], v[76:77], v[28:29], v[80:81]
	v_lshl_add_u64 v[62:63], v[40:41], 0, v[62:63]
	v_lshl_add_u64 v[56:57], v[54:55], 0, s[12:13]
	v_lshl_add_u64 v[54:55], v[54:55], 0, s[14:15]
	v_mov_b32_e32 v65, v64
	v_cvt_pk_bf16_f32 v28, v28, v29
	v_cvt_pk_bf16_f32 v29, v30, v31
	global_store_dwordx2 v[66:67], v[28:29], off
	s_and_saveexec_b64 s[4:5], vcc
	s_cbranch_execz .LBB0_422
	v_mov_b32_e32 v51, v37
	v_lshl_add_u64 v[28:29], v[56:57], 0, v[50:51]
	global_load_dwordx4 v[28:31], v[28:29], off
	v_lshl_add_u64 v[76:77], v[54:55], 0, v[50:51]
	global_load_dwordx4 v[76:79], v[76:77], off
	v_mov_b32_e32 v80, v64
	v_mov_b32_e32 v81, v64
	v_pk_mul_f32 v[24:25], v[24:25], v[64:65]
	v_pk_mul_f32 v[26:27], v[26:27], v[80:81]
	v_pk_mul_f32 v[24:25], v[32:33], v[24:25]
	v_pk_mul_f32 v[26:27], v[34:35], v[26:27]
	s_waitcnt vmcnt(1)
	v_pk_add_f32 v[30:31], v[30:31], 1.0 op_sel_hi:[1,0]
	v_pk_add_f32 v[28:29], v[28:29], 1.0 op_sel_hi:[1,0]
	s_waitcnt vmcnt(0)
	v_pk_fma_f32 v[26:27], v[26:27], v[30:31], v[78:79]
	v_pk_fma_f32 v[24:25], v[24:25], v[28:29], v[76:77]
	s_nop 0
	v_cvt_pk_bf16_f32 v24, v24, v25
	v_cvt_pk_bf16_f32 v25, v26, v27
	global_store_dwordx2 v[62:63], v[24:25], off

.LBB0_1262:
	v_add_u32_e32 v75, s94, v54
	v_mov_b32_e32 v100, v54
	v_xor_b32_e32 v102, 0xc000, v100
	v_and_b32_e32 v103, 0x7ff, v100
	v_lshrrev_b32_e32 v102, 3, v102
	v_lshlrev_b32_e32 v54, 2, v100
	v_and_b32_e32 v102, 0x1800, v102
	v_and_b32_e32 v54, 0xe000, v54
	v_or3_b32 v54, v54, v102, v103
	v_ashrrev_i32_e32 v55, 31, v54
	v_lshlrev_b64 v[0:1], 12, v[54:55]
	v_cmp_gt_i32_e32 vcc, s2, v75
	v_lshl_add_u64 v[0:1], v[38:39], 0, v[0:1]
	global_load_dwordx4 v[28:31], v[0:1], off nt
	global_load_dwordx4 v[20:23], v[0:1], off offset:1024 nt
	global_load_dwordx4 v[4:7], v[0:1], off offset:3072 nt
	global_load_dwordx4 v[12:15], v[0:1], off offset:2048 nt
	v_xor_b32_e32 v102, 0xc000, v75
	v_and_b32_e32 v103, 0x7ff, v75
	v_lshrrev_b32_e32 v102, 3, v102
	v_lshlrev_b32_e32 v101, 2, v75
	v_and_b32_e32 v102, 0x1800, v102
	v_and_b32_e32 v101, 0xe000, v101
	v_or3_b32 v101, v101, v102, v103
	v_cndmask_b32_e32 v56, v54, v101, vcc
	v_ashrrev_i32_e32 v57, 31, v56
	v_lshlrev_b64 v[0:1], 12, v[56:57]
	v_lshl_add_u64 v[32:33], v[38:39], 0, v[0:1]
	global_load_dwordx4 v[24:27], v[32:33], off nt
	global_load_dwordx4 v[16:19], v[32:33], off offset:1024 nt
	global_load_dwordx4 v[0:3], v[32:33], off offset:3072 nt
	global_load_dwordx4 v[8:11], v[32:33], off offset:2048 nt
	s_waitcnt vmcnt(7)
	v_pk_mul_f32 v[32:33], v[30:31], v[30:31]
	v_pk_mul_f32 v[34:35], v[28:29], v[28:29]
	s_waitcnt vmcnt(6)
	v_pk_mul_f32 v[58:59], v[22:23], v[22:23]
	v_pk_mul_f32 v[60:61], v[20:21], v[20:21]
	s_waitcnt vmcnt(4)
	v_mul_f32_e32 v62, v15, v15
	v_pk_mov_b32 v[64:65], v[34:35], v[32:33] op_sel:[1,0]
	v_mov_b32_e32 v35, v33
	v_pk_mov_b32 v[32:33], v[60:61], v[58:59] op_sel:[1,0]
	v_mov_b32_e32 v61, v59
	v_mul_f32_e32 v78, v7, v7
	v_mul_f32_e32 v36, v13, v13
	v_pk_fma_f32 v[62:63], v[14:15], v[14:15], v[62:63] op_sel_hi:[1,1,0]
	v_pk_add_f32 v[34:35], v[64:65], v[34:35]
	s_waitcnt vmcnt(3)
	v_pk_mul_f32 v[64:65], v[26:27], v[26:27]
	v_pk_mul_f32 v[66:67], v[24:25], v[24:25]
	v_pk_add_f32 v[32:33], v[32:33], v[60:61]
	s_waitcnt vmcnt(2)
	v_pk_mul_f32 v[60:61], v[18:19], v[18:19]
	v_pk_mul_f32 v[68:69], v[16:17], v[16:17]
	v_mul_f32_e32 v51, v4, v4
	v_mul_f32_e32 v77, v5, v5
	v_mul_f32_e32 v76, v6, v6
	v_pk_fma_f32 v[58:59], v[12:13], v[12:13], v[36:37] op_sel_hi:[1,1,0]
	v_mov_b32_e32 v63, v78
	v_pk_mov_b32 v[78:79], v[66:67], v[64:65] op_sel:[1,0]
	v_mov_b32_e32 v67, v65
	v_pk_mov_b32 v[64:65], v[68:69], v[60:61] op_sel:[1,0]
	v_mov_b32_e32 v69, v61
	v_pk_add_f32 v[34:35], v[34:35], v[34:35] op_sel:[0,1] op_sel_hi:[1,0]
	v_pk_add_f32 v[32:33], v[32:33], v[32:33] op_sel:[0,1] op_sel_hi:[1,0]
	v_mov_b32_e32 v59, v76
	s_waitcnt vmcnt(0)
	v_mul_f32_e32 v36, v9, v9
	v_mul_f32_e32 v76, v11, v11
	v_pk_add_f32 v[66:67], v[78:79], v[66:67]
	v_pk_add_f32 v[64:65], v[64:65], v[68:69]
	v_mov_b32_e32 v35, v51
	v_mov_b32_e32 v33, v77
	v_mul_f32_e32 v80, v0, v0
	v_mul_f32_e32 v81, v1, v1
	v_mul_f32_e32 v82, v2, v2
	v_mul_f32_e32 v83, v3, v3
	v_pk_add_f32 v[58:59], v[58:59], v[62:63]
	v_pk_fma_f32 v[60:61], v[8:9], v[8:9], v[36:37] op_sel_hi:[1,1,0]
	v_pk_fma_f32 v[62:63], v[10:11], v[10:11], v[76:77] op_sel_hi:[1,1,0]
	v_pk_add_f32 v[32:33], v[34:35], v[32:33]
	v_pk_add_f32 v[34:35], v[66:67], v[66:67] op_sel:[0,1] op_sel_hi:[1,0]
	v_pk_add_f32 v[64:65], v[64:65], v[64:65] op_sel:[0,1] op_sel_hi:[1,0]
	v_mov_b32_e32 v61, v82
	v_mov_b32_e32 v63, v83
	v_pk_add_f32 v[32:33], v[32:33], v[58:59]
	v_mov_b32_e32 v35, v80
	v_mov_b32_e32 v65, v81
	v_pk_add_f32 v[60:61], v[60:61], v[62:63]
	v_add_f32_e32 v36, v32, v33
	v_pk_add_f32 v[32:33], v[34:35], v[64:65]
	ds_bpermute_b32 v34, v45, v36
	v_pk_add_f32 v[32:33], v[32:33], v[60:61]
	v_ashrrev_i32_e32 v51, 12, v54
	v_add_f32_e32 v32, v32, v33
	ds_bpermute_b32 v33, v45, v32
	s_waitcnt lgkmcnt(1)
	v_add_f32_e32 v36, v36, v34
	ds_bpermute_b32 v58, v47, v36
	v_mul_hi_i32_i24_e32 v59, 0x9000, v51
	s_waitcnt lgkmcnt(1)
	v_add_f32_e32 v60, v32, v33
	ds_bpermute_b32 v61, v47, v60
	s_waitcnt lgkmcnt(1)
	v_add_f32_e32 v36, v36, v58
	ds_bpermute_b32 v62, v49, v36
	v_mul_i32_i24_e32 v58, 0x9000, v51
	v_lshl_add_u64 v[58:59], s[12:13], 0, v[58:59]
	s_waitcnt lgkmcnt(1)
	v_add_f32_e32 v60, v60, v61
	ds_bpermute_b32 v61, v49, v60
	s_waitcnt lgkmcnt(1)
	v_add_f32_e32 v36, v36, v62
	global_load_dwordx4 v[32:35], v[42:43], off
	ds_bpermute_b32 v51, v70, v36
	s_waitcnt lgkmcnt(1)
	v_add_f32_e32 v62, v60, v61
	ds_bpermute_b32 v63, v70, v62
	v_lshl_add_u64 v[60:61], v[58:59], 0, s[14:15]
	v_lshl_add_u64 v[58:59], v[58:59], 0, s[16:17]
	v_lshl_add_u64 v[64:65], v[58:59], 0, v[52:53]
	s_waitcnt lgkmcnt(1)
	v_add_f32_e32 v36, v36, v51
	s_waitcnt lgkmcnt(0)
	v_add_f32_e32 v66, v62, v63
	v_lshl_add_u64 v[62:63], v[60:61], 0, v[52:53]
	global_load_dwordx4 v[76:79], v[62:63], off
	global_load_dwordx4 v[80:83], v[64:65], off
	ds_bpermute_b32 v51, v71, v36
	ds_bpermute_b32 v67, v71, v66
	s_waitcnt lgkmcnt(1)
	v_add_f32_e32 v36, v36, v51
	ds_bpermute_b32 v51, v72, v36
	s_waitcnt lgkmcnt(1)
	v_add_f32_e32 v66, v66, v67
	ds_bpermute_b32 v67, v72, v66
	s_waitcnt lgkmcnt(1)
	v_add_f32_e32 v36, v36, v51
	v_fmamk_f32 v36, v36, 0x3a800000, v73
	v_mul_f32_e32 v51, 0x4f800000, v36
	v_cmp_gt_f32_e32 vcc, s3, v36
	s_waitcnt lgkmcnt(0)
	v_add_f32_e32 v62, v66, v67
	s_waitcnt vmcnt(1)
	v_pk_add_f32 v[78:79], v[78:79], 1.0 op_sel_hi:[1,0]
	v_cndmask_b32_e32 v36, v36, v51, vcc
	v_fmamk_f32 v51, v62, 0x3a800000, v73
	v_sqrt_f32_e32 v62, v36
	v_mul_f32_e32 v63, 0x4f800000, v51
	v_cmp_gt_f32_e64 s[6:7], s3, v51
	v_pk_add_f32 v[76:77], v[76:77], 1.0 op_sel_hi:[1,0]
	v_add_u32_e32 v64, -1, v62
	v_cndmask_b32_e64 v51, v51, v63, s[6:7]
	v_sqrt_f32_e32 v63, v51
	v_add_u32_e32 v65, 1, v62
	v_fma_f32 v66, -v64, v62, v36
	v_fma_f32 v67, -v65, v62, v36
	v_cmp_ge_f32_e64 s[8:9], 0, v66
	v_add_u32_e32 v66, 1, v63
	s_nop 0
	v_cndmask_b32_e64 v62, v62, v64, s[8:9]
	v_add_u32_e32 v64, -1, v63
	v_cmp_lt_f32_e64 s[8:9], 0, v67
	v_fma_f32 v67, -v66, v63, v51
	s_nop 0
	v_cndmask_b32_e64 v62, v62, v65, s[8:9]
	v_fma_f32 v65, -v64, v63, v51
	v_mul_f32_e32 v68, 0x37800000, v62
	v_cmp_ge_f32_e64 s[8:9], 0, v65
	v_cndmask_b32_e32 v62, v62, v68, vcc
	v_cmp_lt_f32_e32 vcc, 0, v67
	v_cndmask_b32_e64 v63, v63, v64, s[8:9]
	s_nop 0
	v_cndmask_b32_e32 v63, v63, v66, vcc
	v_cmp_class_f32_e32 vcc, v36, v74
	s_nop 1
	v_cndmask_b32_e32 v36, v62, v36, vcc
	v_div_scale_f32 v64, s[8:9], v36, v36, 1.0
	v_rcp_f32_e32 v65, v64
	v_mul_f32_e32 v62, 0x37800000, v63
	v_cndmask_b32_e64 v62, v63, v62, s[6:7]
	v_div_scale_f32 v66, vcc, 1.0, v36, 1.0
	v_fma_f32 v63, -v64, v65, 1.0
	v_fmac_f32_e32 v65, v63, v65
	v_mul_f32_e32 v63, v66, v65
	v_cmp_class_f32_e64 s[6:7], v51, v74
	v_fma_f32 v67, -v64, v63, v66
	v_fmac_f32_e32 v63, v67, v65
	v_cndmask_b32_e64 v51, v62, v51, s[6:7]
	v_div_scale_f32 v62, s[6:7], v51, v51, 1.0
	v_fma_f32 v64, -v64, v63, v66
	v_rcp_f32_e32 v66, v62
	v_div_fmas_f32 v63, v64, v65, v63
	v_div_fixup_f32 v68, v63, v36, 1.0
	v_pk_mul_f32 v[30:31], v[30:31], v[68:69] op_sel_hi:[1,0]
	v_fma_f32 v36, -v62, v66, 1.0
	v_fmac_f32_e32 v66, v36, v66
	v_div_scale_f32 v36, vcc, 1.0, v51, 1.0
	v_mul_f32_e32 v63, v36, v66
	v_fma_f32 v64, -v62, v63, v36
	v_fmac_f32_e32 v63, v64, v66
	v_fma_f32 v36, -v62, v63, v36
	v_div_fmas_f32 v36, v36, v66, v63
	v_div_fixup_f32 v64, v36, v51, 1.0
	v_ashrrev_i32_e32 v36, 12, v56
	v_pk_mul_f32 v[28:29], v[28:29], v[68:69] op_sel_hi:[1,0]
	v_lshlrev_b64 v[62:63], 11, v[54:55]
	v_cmp_ne_u32_e32 vcc, v54, v56
	v_mul_hi_i32_i24_e32 v55, 0x9000, v36
	v_mul_i32_i24_e32 v54, 0x9000, v36
	v_pk_mul_f32 v[28:29], v[32:33], v[28:29]
	v_pk_mul_f32 v[30:31], v[34:35], v[30:31]
	v_lshl_add_u64 v[66:67], v[40:41], 0, v[62:63]
	v_lshlrev_b64 v[62:63], 11, v[56:57]
	v_lshl_add_u64 v[54:55], s[12:13], 0, v[54:55]
	s_waitcnt vmcnt(0)
	v_pk_fma_f32 v[30:31], v[78:79], v[30:31], v[82:83]
	v_pk_fma_f32 v[28:29], v[76:77], v[28:29], v[80:81]
	v_lshl_add_u64 v[62:63], v[40:41], 0, v[62:63]
	v_lshl_add_u64 v[56:57], v[54:55], 0, s[14:15]
	v_lshl_add_u64 v[54:55], v[54:55], 0, s[16:17]
	v_mov_b32_e32 v65, v64
	v_cvt_pk_bf16_f32 v28, v28, v29
	v_cvt_pk_bf16_f32 v29, v30, v31
	global_store_dwordx2 v[66:67], v[28:29], off
	s_and_saveexec_b64 s[6:7], vcc
	s_cbranch_execz .LBB0_1264
	v_mov_b32_e32 v51, v37
	v_lshl_add_u64 v[28:29], v[56:57], 0, v[50:51]
	global_load_dwordx4 v[28:31], v[28:29], off
	v_lshl_add_u64 v[76:77], v[54:55], 0, v[50:51]
	global_load_dwordx4 v[76:79], v[76:77], off
	v_mov_b32_e32 v80, v64
	v_mov_b32_e32 v81, v64
	v_pk_mul_f32 v[24:25], v[24:25], v[64:65]
	v_pk_mul_f32 v[26:27], v[26:27], v[80:81]
	v_pk_mul_f32 v[24:25], v[32:33], v[24:25]
	v_pk_mul_f32 v[26:27], v[34:35], v[26:27]
	s_waitcnt vmcnt(1)
	v_pk_add_f32 v[30:31], v[30:31], 1.0 op_sel_hi:[1,0]
	v_pk_add_f32 v[28:29], v[28:29], 1.0 op_sel_hi:[1,0]
	s_waitcnt vmcnt(0)
	v_pk_fma_f32 v[26:27], v[26:27], v[30:31], v[78:79]
	v_pk_fma_f32 v[24:25], v[24:25], v[28:29], v[76:77]
	s_nop 0
	v_cvt_pk_bf16_f32 v24, v24, v25
	v_cvt_pk_bf16_f32 v25, v26, v27
	global_store_dwordx2 v[62:63], v[24:25], off

.LBB0_1473:
	v_add_u32_e32 v100, s94, v44
	v_mov_b32_e32 v104, v44
	v_xor_b32_e32 v102, 0xc000, v104
	v_and_b32_e32 v103, 0x7ff, v104
	v_lshrrev_b32_e32 v102, 3, v102
	v_lshlrev_b32_e32 v44, 2, v104
	v_and_b32_e32 v102, 0x1800, v102
	v_and_b32_e32 v44, 0xe000, v44
	v_or3_b32 v44, v44, v102, v103
	v_ashrrev_i32_e32 v45, 31, v44
	v_lshlrev_b64 v[0:1], 12, v[44:45]
	v_mov_b32_e32 v45, v100
	v_cmp_gt_i32_e32 vcc, s6, v45
	v_lshl_add_u64 v[40:41], v[36:37], 0, v[0:1]
	global_load_dwordx4 v[28:31], v[40:41], off nt
	global_load_dwordx4 v[16:19], v[40:41], off offset:1024 nt
	global_load_dwordx4 v[0:3], v[40:41], off offset:3072 nt
	global_load_dwordx4 v[12:15], v[40:41], off offset:2048 nt
	v_xor_b32_e32 v102, 0xc000, v45
	v_and_b32_e32 v103, 0x7ff, v45
	v_lshrrev_b32_e32 v102, 3, v102
	v_lshlrev_b32_e32 v101, 2, v45
	v_and_b32_e32 v102, 0x1800, v102
	v_and_b32_e32 v101, 0xe000, v101
	v_or3_b32 v101, v101, v102, v103
	v_cndmask_b32_e32 v46, v44, v101, vcc
	v_ashrrev_i32_e32 v47, 31, v46
	v_lshlrev_b64 v[4:5], 12, v[46:47]
	v_lshl_add_u64 v[42:43], v[36:37], 0, v[4:5]
	global_load_dwordx4 v[24:27], v[42:43], off nt
	global_load_dwordx4 v[20:23], v[42:43], off offset:1024 nt
	global_load_dwordx4 v[4:7], v[42:43], off offset:3072 nt
	global_load_dwordx4 v[8:11], v[42:43], off offset:2048 nt
	s_waitcnt vmcnt(7)
	v_pk_mul_f32 v[32:33], v[30:31], v[30:31]
	v_pk_mul_f32 v[34:35], v[28:29], v[28:29]
	s_waitcnt vmcnt(6)
	v_pk_mul_f32 v[48:49], v[18:19], v[18:19]
	v_pk_mul_f32 v[50:51], v[16:17], v[16:17]
	s_waitcnt vmcnt(4)
	v_mul_f32_e32 v60, v13, v13
	v_mul_f32_e32 v62, v15, v15
	v_pk_mov_b32 v[64:65], v[34:35], v[32:33] op_sel:[1,0]
	v_mov_b32_e32 v35, v33
	v_pk_mov_b32 v[32:33], v[50:51], v[48:49] op_sel:[1,0]
	v_mov_b32_e32 v51, v49
	v_pk_fma_f32 v[48:49], v[12:13], v[12:13], v[60:61] op_sel_hi:[1,1,0]
	v_pk_fma_f32 v[60:61], v[14:15], v[14:15], v[62:63] op_sel_hi:[1,1,0]
	v_pk_add_f32 v[34:35], v[64:65], v[34:35]
	s_waitcnt vmcnt(3)
	v_pk_mul_f32 v[62:63], v[26:27], v[26:27]
	v_pk_mul_f32 v[64:65], v[24:25], v[24:25]
	v_pk_add_f32 v[32:33], v[32:33], v[50:51]
	s_waitcnt vmcnt(2)
	v_pk_mul_f32 v[50:51], v[22:23], v[22:23]
	v_pk_mul_f32 v[66:67], v[20:21], v[20:21]
	v_mul_f32_e32 v47, v0, v0
	v_mul_f32_e32 v69, v1, v1
	v_mul_f32_e32 v68, v2, v2
	v_mul_f32_e32 v70, v3, v3
	v_pk_mov_b32 v[72:73], v[64:65], v[62:63] op_sel:[1,0]
	v_mov_b32_e32 v65, v63
	v_pk_mov_b32 v[62:63], v[66:67], v[50:51] op_sel:[1,0]
	v_mov_b32_e32 v67, v51
	v_pk_add_f32 v[34:35], v[34:35], v[34:35] op_sel:[0,1] op_sel_hi:[1,0]
	v_pk_add_f32 v[32:33], v[32:33], v[32:33] op_sel:[0,1] op_sel_hi:[1,0]
	v_mov_b32_e32 v49, v68
	v_mov_b32_e32 v61, v70
	s_waitcnt vmcnt(1)
	v_mul_f32_e32 v71, v4, v4
	s_waitcnt vmcnt(0)
	v_mul_f32_e32 v68, v9, v9
	v_mul_f32_e32 v70, v11, v11
	v_pk_add_f32 v[64:65], v[72:73], v[64:65]
	v_pk_add_f32 v[62:63], v[62:63], v[66:67]
	v_mov_b32_e32 v35, v47
	v_mov_b32_e32 v33, v69
	v_mul_f32_e32 v74, v5, v5
	v_mul_f32_e32 v75, v6, v6
	v_mul_f32_e32 v76, v7, v7
	v_pk_add_f32 v[48:49], v[48:49], v[60:61]
	v_pk_fma_f32 v[50:51], v[8:9], v[8:9], v[68:69] op_sel_hi:[1,1,0]
	v_pk_fma_f32 v[60:61], v[10:11], v[10:11], v[70:71] op_sel_hi:[1,1,0]
	v_pk_add_f32 v[32:33], v[34:35], v[32:33]
	v_pk_add_f32 v[34:35], v[64:65], v[64:65] op_sel:[0,1] op_sel_hi:[1,0]
	v_pk_add_f32 v[62:63], v[62:63], v[62:63] op_sel:[0,1] op_sel_hi:[1,0]
	v_mov_b32_e32 v51, v75
	v_mov_b32_e32 v61, v76
	v_pk_add_f32 v[32:33], v[32:33], v[48:49]
	v_mov_b32_e32 v35, v71
	v_mov_b32_e32 v63, v74
	v_pk_add_f32 v[50:51], v[50:51], v[60:61]
	v_add_f32_e32 v47, v32, v33
	v_pk_add_f32 v[32:33], v[34:35], v[62:63]
	ds_bpermute_b32 v34, v52, v47
	v_pk_add_f32 v[32:33], v[32:33], v[50:51]
	s_waitcnt lgkmcnt(0)
	v_add_f32_e32 v34, v47, v34
	v_add_f32_e32 v32, v32, v33
	ds_bpermute_b32 v33, v52, v32
	ds_bpermute_b32 v35, v53, v34
	s_waitcnt lgkmcnt(1)
	v_add_f32_e32 v32, v32, v33
	ds_bpermute_b32 v33, v53, v32
	s_waitcnt lgkmcnt(1)
	v_add_f32_e32 v34, v34, v35
	ds_bpermute_b32 v35, v54, v34
	s_waitcnt lgkmcnt(1)
	v_add_f32_e32 v32, v32, v33
	ds_bpermute_b32 v33, v54, v32
	s_waitcnt lgkmcnt(1)
	v_add_f32_e32 v47, v34, v35
	ds_bpermute_b32 v48, v55, v47
	s_waitcnt lgkmcnt(1)
	v_add_f32_e32 v49, v32, v33
	global_load_dwordx4 v[32:35], v[38:39], off
	ds_bpermute_b32 v50, v55, v49
	s_waitcnt lgkmcnt(1)
	v_add_f32_e32 v47, v47, v48
	ds_bpermute_b32 v48, v56, v47
	s_waitcnt lgkmcnt(1)
	v_add_f32_e32 v49, v49, v50
	ds_bpermute_b32 v50, v56, v49
	s_waitcnt lgkmcnt(1)
	v_add_f32_e32 v47, v47, v48
	ds_bpermute_b32 v48, v57, v47
	s_waitcnt lgkmcnt(1)
	v_add_f32_e32 v49, v49, v50
	ds_bpermute_b32 v50, v57, v49
	s_waitcnt lgkmcnt(1)
	v_add_f32_e32 v47, v47, v48
	v_fmamk_f32 v47, v47, 0x3a800000, v58
	v_mul_f32_e32 v48, 0x4f800000, v47
	v_cmp_gt_f32_e32 vcc, s7, v47
	s_waitcnt lgkmcnt(0)
	v_add_f32_e32 v49, v49, v50
	v_cndmask_b32_e32 v47, v47, v48, vcc
	v_fmamk_f32 v48, v49, 0x3a800000, v58
	v_sqrt_f32_e32 v49, v47
	v_mul_f32_e32 v50, 0x4f800000, v48
	v_cmp_gt_f32_e64 s[0:1], s7, v48
	v_add_u32_e32 v51, -1, v49
	s_nop 0
	v_cndmask_b32_e64 v48, v48, v50, s[0:1]
	v_sqrt_f32_e32 v50, v48
	v_add_u32_e32 v60, 1, v49
	v_fma_f32 v61, -v51, v49, v47
	v_fma_f32 v62, -v60, v49, v47
	v_cmp_ge_f32_e64 s[2:3], 0, v61
	v_add_u32_e32 v61, 1, v50
	s_nop 0
	v_cndmask_b32_e64 v49, v49, v51, s[2:3]
	v_add_u32_e32 v51, -1, v50
	v_cmp_lt_f32_e64 s[2:3], 0, v62
	v_fma_f32 v62, -v61, v50, v48
	s_nop 0
	v_cndmask_b32_e64 v49, v49, v60, s[2:3]
	v_fma_f32 v60, -v51, v50, v48
	v_mul_f32_e32 v63, 0x37800000, v49
	v_cmp_ge_f32_e64 s[2:3], 0, v60
	v_cndmask_b32_e32 v49, v49, v63, vcc
	v_cmp_lt_f32_e32 vcc, 0, v62
	v_cndmask_b32_e64 v50, v50, v51, s[2:3]
	s_nop 0
	v_cndmask_b32_e32 v50, v50, v61, vcc
	v_cmp_class_f32_e32 vcc, v47, v59
	s_nop 1
	v_cndmask_b32_e32 v47, v49, v47, vcc
	v_mul_f32_e32 v49, 0x37800000, v50
	v_div_scale_f32 v51, s[2:3], v47, v47, 1.0
	v_cndmask_b32_e64 v49, v50, v49, s[0:1]
	v_rcp_f32_e32 v50, v51
	v_cmp_class_f32_e64 s[0:1], v48, v59
	v_div_scale_f32 v60, vcc, 1.0, v47, 1.0
	s_nop 0
	v_cndmask_b32_e64 v48, v49, v48, s[0:1]
	v_div_scale_f32 v49, s[0:1], v48, v48, 1.0
	v_rcp_f32_e32 v62, v49
	v_fma_f32 v63, -v51, v50, 1.0
	v_fmac_f32_e32 v50, v63, v50
	v_mul_f32_e32 v63, v60, v50
	v_fma_f32 v65, -v51, v63, v60
	v_fma_f32 v64, -v49, v62, 1.0
	v_fmac_f32_e32 v63, v65, v50
	v_div_scale_f32 v61, s[0:1], 1.0, v48, 1.0
	v_fmac_f32_e32 v62, v64, v62
	v_fma_f32 v51, -v51, v63, v60
	v_mul_f32_e32 v64, v61, v62
	v_div_fmas_f32 v50, v51, v50, v63
	v_div_fixup_f32 v50, v50, v47, 1.0
	v_fma_f32 v47, -v49, v64, v61
	v_fmac_f32_e32 v64, v47, v62
	v_fma_f32 v47, -v49, v64, v61
	s_mov_b64 vcc, s[0:1]
	v_div_fmas_f32 v47, v47, v62, v64
	v_mov_b32_e32 v51, v50
	v_div_fixup_f32 v48, v47, v48, 1.0
	v_pk_mul_f32 v[28:29], v[28:29], v[50:51] op_sel_hi:[1,0]
	v_pk_mul_f32 v[30:31], v[30:31], v[50:51] op_sel_hi:[1,0]
	v_cmp_ne_u32_e32 vcc, v44, v46
	v_mov_b32_e32 v49, v48
	s_waitcnt vmcnt(0)
	v_pk_mul_f32 v[30:31], v[34:35], v[30:31]
	v_pk_mul_f32 v[28:29], v[32:33], v[28:29]
	v_pk_mul_f32 v[16:17], v[16:17], v[50:51]
	global_store_dwordx4 v[40:41], v[28:31], off nt
	s_and_saveexec_b64 s[0:1], vcc
	s_xor_b64 s[0:1], exec, s[0:1]
	s_cbranch_execz .LBB0_1475
	v_mov_b32_e32 v28, v48
	v_mov_b32_e32 v29, v48
	v_pk_mul_f32 v[26:27], v[26:27], v[28:29]
	v_pk_mul_f32 v[24:25], v[24:25], v[48:49]
	v_pk_mul_f32 v[26:27], v[34:35], v[26:27]
	v_pk_mul_f32 v[24:25], v[32:33], v[24:25]
	global_store_dwordx4 v[42:43], v[24:27], off nt
	global_load_dwordx4 v[24:27], v[38:39], off offset:1024
	v_mov_b32_e32 v30, v50
	v_mov_b32_e32 v31, v50
	v_pk_mul_f32 v[18:19], v[18:19], v[30:31]
	v_pk_mul_f32 v[20:21], v[20:21], v[48:49]
	v_pk_mul_f32 v[22:23], v[22:23], v[28:29]
	s_waitcnt vmcnt(0)
	v_pk_mul_f32 v[18:19], v[18:19], v[26:27]
	v_pk_mul_f32 v[16:17], v[16:17], v[24:25]
	v_pk_mul_f32 v[22:23], v[22:23], v[26:27]
	v_pk_mul_f32 v[20:21], v[20:21], v[24:25]
	global_store_dwordx4 v[40:41], v[16:19], off offset:1024 nt
	global_store_dwordx4 v[42:43], v[20:23], off offset:1024 nt
